# pvprio + score-minus-max subs packed in all 14 remaining attention blocks (incl. bodies that reuse the max register): -56 VALU static
# baseline (speedup 1.0000x reference)
; #define LAS __attribute__((address_space(3)))
; #define GAS __attribute__((address_space(1)))
; template <int MODE> ...
;     ...
;     auto head = [&](const int t) __attribute__((always_inline)) {
;         if (t >= 2) { if (t + 1 < nT || nK) asm volatile("s_waitcnt vmcnt(2)" ::: "memory"); else asm volatile("s_waitcnt vmcnt(0)" ::: "memory"); }
;         __builtin_amdgcn_s_barrier();
;         if (t + 2 < nT) DMA_TILE(t + 2); else if (nK) DMA_NEXT(t + 2 - nT);
;     };
;     auto body = [&](const int t) __attribute__((always_inline)) {
;         if (t >= act0 && t < act0 + actn) {
;         const LAS unsigned char* Sl = ring + ((t + base) % 3) * SLOT;
; #pragma unroll
;         for (int hf = 0; hf < NH; ++hf) {
;             if (MODE == 1) { const int ks = ktok0 + 64 * t + 32 * hf;
;                 if (ks + 31 < qtok0 - 128 || ks > qtok0 + 31 + 128) continue; }
;             bf16x8 kf[2][2][2];
; #pragma unroll
;             for (int jj = 0; jj < 2; ++jj)
; #pragma unroll
;                 for (int kt = 0; kt < 2; ++kt)
; #pragma unroll
;                     for (int ks = 0; ks < 2; ++ks) kf[jj][kt][ks] = *(const LAS bf16x8*)(Sl + kad[jj][ks] + (32 * hf + 16 * kt) * 128);
;             f32x4 bb[2][2];
; #pragma unroll
;             for (int jj = 0; jj < 2; ++jj) { const LAS f32x4* bl = bcp + ((MODE == 0) ? (dr0 + t - act0) * 8 : 16 * t + 8 * hf) + bofs[jj];
; #pragma unroll
;                 for (int kt = 0; kt < 2; ++kt) bb[jj][kt] = bl[4 * kt]; }
;             s16x4 vlo[2][4], vhi[2][4];
; #pragma unroll
;             for (int jj = 0; jj < 2; ++jj)
; #pragma unroll
;                 for (int dt = 0; dt < 4; ++dt) { const LAS unsigned char* vp = Sl + vad[jj] + (32 * hf) * 128 + ((dt ^ sv) << 5);
;                     vlo[jj][dt] = __builtin_bit_cast(s16x4, __builtin_amdgcn_ds_read_tr16_b64_v4i16((LAS s16x4*)(vp)));
;                     vhi[jj][dt] = __builtin_bit_cast(s16x4, __builtin_amdgcn_ds_read_tr16_b64_v4i16((LAS s16x4*)(vp + 2048))); }
;     ...
;     bf16x8 qn[2][2];
;     { const GAS bf16_t* qs = nQ ? (const GAS bf16_t*)nQ : (const GAS bf16_t*)proj + (size_t)qtok0 * NIN + qcol;
; #pragma unroll
;       for (int jj = 0; jj < 2; ++jj)
; #pragma unroll
;           for (int ks = 0; ks < 2; ++ks) qn[jj][ks] = *(const GAS bf16x8*)(qs + (size_t)(16 * jj) * NIN + 32 * ks + qoff); }
.LBB0_283:
	s_add_i32 s42, s86, s26
	s_add_i32 s0, s42, 1
	s_mul_hi_i32 s14, s0, 0x55555556
	s_lshr_b32 s15, s14, 31
	s_add_i32 s14, s14, s15
	s_mul_i32 s14, s14, 3
	s_sub_i32 s0, s0, s14
	s_lshl_b32 s0, s0, 14
	s_add_i32 s0, s0, s94
	s_add_u32 s34, s34, 0x48000
	s_addc_u32 s35, s35, 0
	s_add_u32 s30, s30, 0x48000
	s_barrier
	s_addc_u32 s31, s31, 0
	s_mov_b32 m0, s0
	s_nop 0
	global_load_lds_dwordx4 v84, s[34:35]
	s_add_u32 m0, m0, 0x2000
	s_nop 0
	global_load_lds_dwordx4 v85, s[30:31]
	v_lshl_add_u64 v[6:7], v[82:83], 1, s[38:39]
	global_load_dwordx4 v[2:5], v[6:7], off
	global_load_dwordx4 v[10:13], v[6:7], off offset:64
	v_add_co_u32_e32 v6, vcc, 0x12000, v6
	s_cmp_gt_u32 s40, s27
	s_nop 0
	v_addc_co_u32_e32 v7, vcc, 0, v7, vcc
	global_load_dwordx4 v[14:17], v[6:7], off
	s_nop 0
	global_load_dwordx4 v[6:9], v[6:7], off offset:64
	s_cselect_b64 s[30:31], -1, 0
	s_add_i32 s0, s23, 8
	s_cmp_le_i32 s26, s0
	s_cselect_b64 s[26:27], -1, 0
	s_and_b64 s[26:27], s[30:31], s[26:27]
	s_and_b64 vcc, exec, s[26:27]
	s_cbranch_vccz .LBB0_285
	s_add_i32 s0, s41, s86
	s_mul_hi_i32 s14, s0, 0x55555556
	s_lshr_b32 s15, s14, 31
	s_add_i32 s14, s14, s15
	s_mul_i32 s14, s14, 3
	s_sub_i32 s0, s0, s14
	s_lshl_b32 s0, s0, 14
	s_sub_i32 s14, s41, s23
	s_add_i32 s0, s0, 0
	s_add_i32 s14, s14, s25
	v_add_u32_e32 v0, s0, v89
	s_lshl_b32 s14, s14, 7
	v_add_u32_e32 v66, s0, v88
	ds_read_b128 v[126:129], v0
	ds_read_b128 v[130:133], v0 offset:2048
	ds_read_b128 v[134:137], v66
	ds_read_b128 v[138:141], v66 offset:2048
	v_add_u32_e32 v0, s0, v92
	s_add_i32 s24, s24, s14
	v_add_u32_e32 v66, s0, v91
	ds_read_b128 v[142:145], v0
	ds_read_b128 v[146:149], v0 offset:2048
	ds_read_b128 v[150:153], v66
	ds_read_b128 v[154:157], v66 offset:2048
	v_lshl_add_u32 v0, v87, 4, s24
	ds_read_b128 v[158:161], v0
	ds_read_b128 v[162:165], v0 offset:64
	v_lshl_add_u32 v0, v90, 4, s24
	ds_read_b128 v[166:169], v0
	ds_read_b128 v[170:173], v0 offset:64
	v_lshlrev_b32_e32 v0, 5, v93
	v_add3_u32 v66, v86, v122, s0
	v_add_u32_e32 v67, v66, v0
	v_xor_b32_e32 v68, 32, v0
	v_add_u32_e32 v69, v66, v68
	ds_read_b64_tr_b16 v[94:95], v67 offset:8192
	ds_read_b64_tr_b16 v[96:97], v67 offset:10240
	ds_read_b64_tr_b16 v[90:91], v69 offset:8192
	ds_read_b64_tr_b16 v[92:93], v69 offset:10240
	v_xor_b32_e32 v67, 64, v0
	v_xor_b32_e32 v70, 0x60, v0
	v_add_u32_e32 v69, v66, v67
	v_add_u32_e32 v66, v66, v70
	ds_read_b64_tr_b16 v[86:87], v69 offset:8192
	ds_read_b64_tr_b16 v[88:89], v69 offset:10240
	ds_read_b64_tr_b16 v[82:83], v66 offset:8192
	ds_read_b64_tr_b16 v[84:85], v66 offset:10240
	v_add3_u32 v66, v123, v122, s0
	v_add_u32_e32 v0, v66, v0
	v_add_u32_e32 v68, v66, v68
	ds_read_b64_tr_b16 v[78:79], v0 offset:8192
	ds_read_b64_tr_b16 v[80:81], v0 offset:10240
	ds_read_b64_tr_b16 v[74:75], v68 offset:8192
	ds_read_b64_tr_b16 v[76:77], v68 offset:10240
	v_add_u32_e32 v0, v66, v67
	v_add_u32_e32 v68, v66, v70
	ds_read_b64_tr_b16 v[70:71], v0 offset:8192
	ds_read_b64_tr_b16 v[72:73], v0 offset:10240
	ds_read_b64_tr_b16 v[66:67], v68 offset:8192
	ds_read_b64_tr_b16 v[68:69], v68 offset:10240
	s_waitcnt lgkmcnt(14)
; __device__ __forceinline__ unsigned cvtpk(float lo, float hi) { f32x2 v = {lo, hi}; bf16x2_t b = __builtin_convertvector(v, bf16x2_t); return __builtin_bit_cast(unsigned, b); }
; __device__ __forceinline__ float vmax3(float a, float b, float c) { return __builtin_elementwise_maximum(__builtin_elementwise_maximum(a, b), c); }
; template <int MODE> ...
;     ...
;             f32x4 s[2][2];
; #pragma unroll
;             for (int jj = 0; jj < 2; ++jj)
; #pragma unroll
;                 for (int kt = 0; kt < 2; ++kt) { f32x4 a = (MODE == 0) ? bb[jj][kt] + mneg[jj][kt] : bb[jj][kt];
;                     a = __builtin_amdgcn_mfma_f32_16x16x32_bf16(kf[jj][kt][0], qf[jj][0], a, 0, 0, 0);
;                     s[jj][kt] = __builtin_amdgcn_mfma_f32_16x16x32_bf16(kf[jj][kt][1], qf[jj][1], a, 0, 0, 0); }
;             u32x4 pw[2];
; #pragma unroll
;             for (int jj = 0; jj < 2; ++jj) {
;                 const float tm = vmax3(vmax3(s[jj][0][0], s[jj][0][1], s[jj][0][2]), vmax3(s[jj][0][3], s[jj][1][0], s[jj][1][1]), vmax3(s[jj][1][2], s[jj][1][3], s[jj][1][3]));
;                 const float mn = quad_max3(mrun[jj], tm);
;                 const float alpha = __builtin_amdgcn_exp2f(mrun[jj] - mn);
;                 mrun[jj] = mn;
;                 float rsum = 0.f;
; #pragma unroll
;                 for (int kt = 0; kt < 2; ++kt)
; #pragma unroll
;                     for (int e = 0; e < 4; ++e) { s[jj][kt][e] = __builtin_amdgcn_exp2f(s[jj][kt][e] - mn); rsum += s[jj][kt][e]; }
;                 lrun[jj] = lrun[jj] * alpha + rsum;
; #pragma unroll
;                 for (int dt = 0; dt < 4; ++dt) o[jj][dt] *= alpha;
;                 pw[jj].x = cvtpk(s[jj][0][0], s[jj][0][1]); pw[jj].y = cvtpk(s[jj][0][2], s[jj][0][3]); pw[jj].z = cvtpk(s[jj][1][0], s[jj][1][1]); pw[jj].w = cvtpk(s[jj][1][2], s[jj][1][3]);
;             }
; #pragma unroll
;             for (int jj = 0; jj < 2; ++jj)
; #pragma unroll
;                 for (int dt = 0; dt < 4; ++dt) {
;                     const bf16x8 vf = (bf16x8){vlo[jj][dt][0], vlo[jj][dt][1], vlo[jj][dt][2], vlo[jj][dt][3], vhi[jj][dt][0], vhi[jj][dt][1], vhi[jj][dt][2], vhi[jj][dt][3]};
;                     o[jj][dt] = __builtin_amdgcn_mfma_f32_16x16x32_bf16(vf, __builtin_bit_cast(bf16x8, pw[jj]), o[jj][dt], 0, 0, 0); }
;             __builtin_amdgcn_sched_barrier(0);
	v_pk_add_f32 v[112:113], v[112:113], v[160:161]
	v_pk_add_f32 v[110:111], v[110:111], v[158:159]
	v_pk_add_f32 v[114:115], v[114:115], v[164:165]
	v_pk_add_f32 v[100:101], v[100:101], v[170:171]
	v_mfma_f32_16x16x32_bf16 v[110:113], v[126:129], v[30:33], v[110:113]
	v_mfma_f32_16x16x32_bf16 v[126:129], v[134:137], v[26:29], v[110:113]
	s_nop 6
	v_pk_add_f32 v[112:113], v[108:109], v[162:163]
	v_maximum3_f32 v0, v126, v127, v128
	v_pk_add_f32 v[108:109], v[106:107], v[168:169]
	v_mfma_f32_16x16x32_bf16 v[30:33], v[130:133], v[30:33], v[112:115]
	v_pk_add_f32 v[106:107], v[102:103], v[166:167]
	v_pk_add_f32 v[102:103], v[104:105], v[172:173]
	v_mfma_f32_16x16x32_bf16 v[26:29], v[138:141], v[26:29], v[30:33]
	s_nop 7
	v_maximum3_f32 v30, v129, v26, v27
	v_maximum3_f32 v31, v28, v29, v29
	v_maximum3_f32 v0, v0, v30, v31
	v_mov_b32_e32 v104, v0
	s_nop 1
	v_permlane16_swap_b32_e32 v0, v104
	v_mfma_f32_16x16x32_bf16 v[30:33], v[142:145], v[22:25], v[106:109]
	v_maximum3_f32 v0, v0, v104, v104
	v_mov_b32_e32 v104, v0
	s_nop 1
	v_permlane32_swap_b32_e32 v0, v104
	v_mfma_f32_16x16x32_bf16 v[22:25], v[146:149], v[22:25], v[100:103]
	v_maximum3_f32 v0, v125, v0, v104
	v_mfma_f32_16x16x32_bf16 v[30:33], v[150:153], v[18:21], v[30:33]
	s_nop 0
	v_sub_f32_e32 v100, v125, v0
	v_exp_f32_e32 v122, v100
	v_pk_add_f32 v[200:201], v[26:27], v[0:1] op_sel_hi:[1,0] neg_lo:[0,1] neg_hi:[0,1]
	v_pk_add_f32 v[202:203], v[28:29], v[0:1] op_sel_hi:[1,0] neg_lo:[0,1] neg_hi:[0,1]
	v_pk_add_f32 v[204:205], v[126:127], v[0:1] op_sel_hi:[1,0] neg_lo:[0,1] neg_hi:[0,1]
	v_pk_add_f32 v[206:207], v[128:129], v[0:1] op_sel_hi:[1,0] neg_lo:[0,1] neg_hi:[0,1]
	v_mfma_f32_16x16x32_bf16 v[18:21], v[154:157], v[18:21], v[22:25]
	v_exp_f32_e32 v104, v204
	v_pk_mul_f32 v[60:61], v[60:61], v[122:123] op_sel_hi:[1,0]
	v_pk_mul_f32 v[58:59], v[58:59], v[122:123] op_sel_hi:[1,0]
	v_exp_f32_e32 v106, v205
	v_exp_f32_e32 v108, v206
	v_exp_f32_e32 v110, v207
	v_exp_f32_e32 v112, v200
	v_exp_f32_e32 v114, v201
	v_exp_f32_e32 v126, v202
	v_exp_f32_e32 v128, v203
	v_pk_mul_f32 v[22:23], v[54:55], v[122:123] op_sel_hi:[1,0]
	v_maximum3_f32 v0, v30, v31, v32
	v_maximum3_f32 v54, v33, v18, v19
	v_maximum3_f32 v55, v20, v21, v21
	v_maximum3_f32 v0, v0, v54, v55
	v_mov_b32_e32 v54, v0
	s_nop 1
	v_permlane16_swap_b32_e32 v0, v54
	v_maximum3_f32 v0, v0, v54, v54
	v_mov_b32_e32 v54, v0
	s_nop 1
	v_permlane32_swap_b32_e32 v0, v54
	v_maximum3_f32 v0, v124, v0, v54
	v_pk_add_f32 v[208:209], v[18:19], v[0:1] op_sel_hi:[1,0] neg_lo:[0,1] neg_hi:[0,1]
	v_pk_add_f32 v[210:211], v[20:21], v[0:1] op_sel_hi:[1,0] neg_lo:[0,1] neg_hi:[0,1]
	v_pk_add_f32 v[212:213], v[30:31], v[0:1] op_sel_hi:[1,0] neg_lo:[0,1] neg_hi:[0,1]
	v_pk_add_f32 v[214:215], v[32:33], v[0:1] op_sel_hi:[1,0] neg_lo:[0,1] neg_hi:[0,1]
	v_exp_f32_e32 v105, v212
	v_exp_f32_e32 v107, v213
	v_exp_f32_e32 v109, v214
	v_exp_f32_e32 v113, v208
	v_sub_f32_e32 v54, v124, v0
	v_exp_f32_e32 v111, v215
	v_exp_f32_e32 v115, v209
	v_pk_mul_f32 v[24:25], v[56:57], v[122:123] op_sel_hi:[1,0]
	v_pk_mul_f32 v[28:29], v[64:65], v[122:123] op_sel_hi:[1,0]
	v_pk_mul_f32 v[26:27], v[62:63], v[122:123] op_sel_hi:[1,0]
	v_pk_mul_f32 v[52:53], v[52:53], v[122:123] op_sel_hi:[1,0]
	v_pk_mul_f32 v[50:51], v[50:51], v[122:123] op_sel_hi:[1,0]
	v_exp_f32_e32 v127, v210
	v_exp_f32_e32 v123, v54
	v_pk_add_f32 v[18:19], v[104:105], 0 op_sel_hi:[1,0]
	v_exp_f32_e32 v129, v211
	v_pk_add_f32 v[18:19], v[106:107], v[18:19]
	v_cvt_pk_bf16_f32 v100, v104, v106
	v_pk_add_f32 v[18:19], v[108:109], v[18:19]
	v_cvt_pk_bf16_f32 v101, v108, v110
	v_pk_add_f32 v[18:19], v[110:111], v[18:19]
	v_cvt_pk_bf16_f32 v102, v112, v114
	v_cvt_pk_bf16_f32 v103, v126, v128
	v_pk_add_f32 v[18:19], v[112:113], v[18:19]
	v_mov_b32_e32 v0, v123
	v_mfma_f32_16x16x32_bf16 v[54:57], v[94:97], v[100:103], v[22:25]
	v_pk_mul_f32 v[20:21], v[48:49], v[0:1] op_sel_hi:[1,0]
	s_setprio 1
	s_waitcnt lgkmcnt(12)
	v_mfma_f32_16x16x32_bf16 v[62:65], v[90:93], v[100:103], v[26:29]
	v_cvt_pk_bf16_f32 v22, v105, v107
	v_cvt_pk_bf16_f32 v23, v109, v111
	v_cvt_pk_bf16_f32 v24, v113, v115
	v_pk_add_f32 v[26:27], v[114:115], v[18:19]
	v_pk_mul_f32 v[18:19], v[46:47], v[0:1] op_sel_hi:[1,0]
	v_cvt_pk_bf16_f32 v25, v127, v129
	s_waitcnt lgkmcnt(10)
	v_mfma_f32_16x16x32_bf16 v[58:61], v[86:89], v[100:103], v[58:61]
	v_pk_add_f32 v[26:27], v[126:127], v[26:27]
	v_pk_add_f32 v[26:27], v[128:129], v[26:27]
	s_waitcnt lgkmcnt(6)
	v_mfma_f32_16x16x32_bf16 v[46:49], v[78:81], v[22:25], v[18:21]
	v_fma_f32 v98, v98, v122, v26
	v_fma_f32 v99, v99, v123, v27
	s_nop 0
	v_pk_mul_f32 v[20:21], v[44:45], v[0:1] op_sel_hi:[1,0]
	v_pk_mul_f32 v[18:19], v[42:43], v[0:1] op_sel_hi:[1,0]
	v_mfma_f32_16x16x32_bf16 v[50:53], v[82:85], v[100:103], v[50:53]
	s_waitcnt lgkmcnt(4)
	v_mfma_f32_16x16x32_bf16 v[42:45], v[74:77], v[22:25], v[18:21]
	s_nop 2
	v_pk_mul_f32 v[20:21], v[40:41], v[0:1] op_sel_hi:[1,0]
	v_pk_mul_f32 v[18:19], v[38:39], v[0:1] op_sel_hi:[1,0]
	s_waitcnt lgkmcnt(2)
	s_nop 0
	v_mfma_f32_16x16x32_bf16 v[38:41], v[70:73], v[22:25], v[18:21]
	s_nop 2
	v_pk_mul_f32 v[20:21], v[36:37], v[0:1] op_sel_hi:[1,0]
	v_pk_mul_f32 v[18:19], v[34:35], v[0:1] op_sel_hi:[1,0]
	s_waitcnt lgkmcnt(0)
	s_setprio 0
	s_nop 0
	v_mfma_f32_16x16x32_bf16 v[34:37], v[66:69], v[22:25], v[18:21]

; #define LAS __attribute__((address_space(3)))
; template <int MODE> ...
;     ...
;             if (MODE == 1) { const int ks = ktok0 + 64 * t + 32 * hf;
;                 if (ks + 31 < qtok0 - 128 || ks > qtok0 + 31 + 128) continue; }
;             bf16x8 kf[2][2][2];
; #pragma unroll
;             for (int jj = 0; jj < 2; ++jj)
; #pragma unroll
;                 for (int kt = 0; kt < 2; ++kt)
; #pragma unroll
;                     for (int ks = 0; ks < 2; ++ks) kf[jj][kt][ks] = *(const LAS bf16x8*)(Sl + kad[jj][ks] + (32 * hf + 16 * kt) * 128);
;             f32x4 bb[2][2];
; #pragma unroll
;             for (int jj = 0; jj < 2; ++jj) { const LAS f32x4* bl = bcp + ((MODE == 0) ? (dr0 + t - act0) * 8 : 16 * t + 8 * hf) + bofs[jj];
; #pragma unroll
;                 for (int kt = 0; kt < 2; ++kt) bb[jj][kt] = bl[4 * kt]; }
;             s16x4 vlo[2][4], vhi[2][4];
; #pragma unroll
;             for (int jj = 0; jj < 2; ++jj)
; #pragma unroll
;                 for (int dt = 0; dt < 4; ++dt) { const LAS unsigned char* vp = Sl + vad[jj] + (32 * hf) * 128 + ((dt ^ sv) << 5);
;                     vlo[jj][dt] = __builtin_bit_cast(s16x4, __builtin_amdgcn_ds_read_tr16_b64_v4i16((LAS s16x4*)(vp)));
;                     vhi[jj][dt] = __builtin_bit_cast(s16x4, __builtin_amdgcn_ds_read_tr16_b64_v4i16((LAS s16x4*)(vp + 2048))); }
;             __builtin_amdgcn_sched_barrier(0);
;             f32x4 s[2][2];
; #pragma unroll
;             for (int jj = 0; jj < 2; ++jj)
; #pragma unroll
;                 for (int kt = 0; kt < 2; ++kt) { f32x4 a = (MODE == 0) ? bb[jj][kt] + mneg[jj][kt] : bb[jj][kt];
;                     a = __builtin_amdgcn_mfma_f32_16x16x32_bf16(kf[jj][kt][0], qf[jj][0], a, 0, 0, 0);
;                     s[jj][kt] = __builtin_amdgcn_mfma_f32_16x16x32_bf16(kf[jj][kt][1], qf[jj][1], a, 0, 0, 0); }
;             u32x4 pw[2];
; #pragma unroll
;             for (int jj = 0; jj < 2; ++jj) {
;                 const float tm = vmax3(vmax3(s[jj][0][0], s[jj][0][1], s[jj][0][2]), vmax3(s[jj][0][3], s[jj][1][0], s[jj][1][1]), vmax3(s[jj][1][2], s[jj][1][3], s[jj][1][3]));
;                 const float mn = quad_max3(mrun[jj], tm);
;                 const float alpha = __builtin_amdgcn_exp2f(mrun[jj] - mn);
;                 mrun[jj] = mn;
;                 float rsum = 0.f;
; #pragma unroll
;                 for (int kt = 0; kt < 2; ++kt)
; #pragma unroll
.LBB0_359:
	s_or_b32 s0, s30, 32
	s_add_i32 s0, s0, s24
	s_or_b32 s14, s0, 31
	s_cmp_lt_i32 s14, s31
	s_cselect_b64 s[30:31], -1, 0
	s_cmp_gt_i32 s0, s25
	s_cselect_b64 s[24:25], -1, 0
	s_or_b64 s[24:25], s[30:31], s[24:25]
	s_and_b64 vcc, exec, s[24:25]
	s_cbranch_vccnz .LBB0_361
	s_add_i32 s27, s27, s26
	v_lshl_add_u32 v83, v93, 4, s27
	ds_read_b128 v[66:69], v100 offset:4096
	ds_read_b128 v[70:73], v100 offset:6144
	ds_read_b128 v[74:77], v99 offset:4096
	ds_read_b128 v[78:81], v99 offset:6144
	ds_read_b128 v[100:103], v83 offset:128
	ds_read_b128 v[104:107], v83 offset:192
	v_lshl_add_u32 v83, v94, 4, s27
	ds_read_b128 v[108:111], v83 offset:128
	ds_read_b128 v[112:115], v83 offset:192
	ds_read_b64_tr_b16 v[118:119], v98 offset:12288
	ds_read_b64_tr_b16 v[120:121], v98 offset:14336
	ds_read_b64_tr_b16 v[122:123], v97 offset:12288
	ds_read_b64_tr_b16 v[124:125], v97 offset:14336
	ds_read_b64_tr_b16 v[126:127], v0 offset:12288
	ds_read_b64_tr_b16 v[128:129], v0 offset:14336
	ds_read_b64_tr_b16 v[130:131], v96 offset:12288
	ds_read_b64_tr_b16 v[132:133], v96 offset:14336
	s_waitcnt lgkmcnt(11)
	v_mfma_f32_16x16x32_bf16 v[96:99], v[66:69], v[30:33], v[100:103]
	s_waitcnt lgkmcnt(10)
	v_mfma_f32_16x16x32_bf16 v[30:33], v[70:73], v[30:33], v[104:107]
	v_mfma_f32_16x16x32_bf16 v[96:99], v[74:77], v[26:29], v[96:99]
	v_mfma_f32_16x16x32_bf16 v[26:29], v[78:81], v[26:29], v[30:33]
	s_nop 6
	v_maximum3_f32 v0, v96, v97, v98
	v_maximum3_f32 v30, v99, v26, v27
	v_maximum3_f32 v31, v28, v29, v29
	v_maximum3_f32 v0, v0, v30, v31
	v_mov_b32_e32 v30, v0
	s_nop 1
	v_permlane16_swap_b32_e32 v0, v30
	v_maximum3_f32 v0, v0, v30, v30
	v_mov_b32_e32 v30, v0
	s_nop 1
	v_permlane32_swap_b32_e32 v0, v30
	v_maximum3_f32 v0, v82, v0, v30
	s_waitcnt lgkmcnt(9)
	v_mfma_f32_16x16x32_bf16 v[30:33], v[66:69], v[22:25], v[108:111]
	v_sub_f32_e32 v83, v82, v0
	v_pk_add_f32 v[200:201], v[26:27], v[0:1] op_sel_hi:[1,0] neg_lo:[0,1] neg_hi:[0,1]
	v_pk_add_f32 v[202:203], v[28:29], v[0:1] op_sel_hi:[1,0] neg_lo:[0,1] neg_hi:[0,1]
	v_pk_add_f32 v[204:205], v[96:97], v[0:1] op_sel_hi:[1,0] neg_lo:[0,1] neg_hi:[0,1]
	v_pk_add_f32 v[206:207], v[98:99], v[0:1] op_sel_hi:[1,0] neg_lo:[0,1] neg_hi:[0,1]
	v_exp_f32_e32 v84, v205
	s_waitcnt lgkmcnt(8)
	v_mfma_f32_16x16x32_bf16 v[22:25], v[70:73], v[22:25], v[112:115]
	v_mfma_f32_16x16x32_bf16 v[30:33], v[74:77], v[18:21], v[30:33]
	v_exp_f32_e32 v74, v206
	v_exp_f32_e32 v82, v204
	v_mfma_f32_16x16x32_bf16 v[18:21], v[78:81], v[18:21], v[22:25]
	v_exp_f32_e32 v78, v83
	v_exp_f32_e32 v70, v207
	v_exp_f32_e32 v72, v200
	v_exp_f32_e32 v76, v201
	v_exp_f32_e32 v80, v202
	v_exp_f32_e32 v94, v203
	v_pk_mul_f32 v[22:23], v[50:51], v[78:79] op_sel_hi:[1,0]
	v_maximum3_f32 v0, v30, v31, v32
	v_maximum3_f32 v50, v33, v18, v19
	v_maximum3_f32 v51, v20, v21, v21
	v_maximum3_f32 v0, v0, v50, v51
	v_mov_b32_e32 v50, v0
	s_nop 1
	v_permlane16_swap_b32_e32 v0, v50
	v_maximum3_f32 v0, v0, v50, v50
	v_mov_b32_e32 v50, v0
	s_nop 1
	v_permlane32_swap_b32_e32 v0, v50
	v_maximum3_f32 v0, v95, v0, v50
	v_pk_add_f32 v[208:209], v[18:19], v[0:1] op_sel_hi:[1,0] neg_lo:[0,1] neg_hi:[0,1]
	v_pk_add_f32 v[210:211], v[20:21], v[0:1] op_sel_hi:[1,0] neg_lo:[0,1] neg_hi:[0,1]
	v_pk_add_f32 v[212:213], v[30:31], v[0:1] op_sel_hi:[1,0] neg_lo:[0,1] neg_hi:[0,1]
	v_pk_add_f32 v[214:215], v[32:33], v[0:1] op_sel_hi:[1,0] neg_lo:[0,1] neg_hi:[0,1]
	v_exp_f32_e32 v83, v212
	v_exp_f32_e32 v85, v213
	v_exp_f32_e32 v75, v214
	v_exp_f32_e32 v73, v208
	v_sub_f32_e32 v50, v95, v0
	v_exp_f32_e32 v71, v215
	v_exp_f32_e32 v77, v209
	v_pk_mul_f32 v[24:25], v[52:53], v[78:79] op_sel_hi:[1,0]
	v_pk_mul_f32 v[28:29], v[56:57], v[78:79] op_sel_hi:[1,0]
	v_pk_mul_f32 v[26:27], v[54:55], v[78:79] op_sel_hi:[1,0]
	v_pk_mul_f32 v[60:61], v[60:61], v[78:79] op_sel_hi:[1,0]
	v_pk_mul_f32 v[58:59], v[58:59], v[78:79] op_sel_hi:[1,0]
	v_pk_mul_f32 v[64:65], v[64:65], v[78:79] op_sel_hi:[1,0]
	v_pk_mul_f32 v[62:63], v[62:63], v[78:79] op_sel_hi:[1,0]
	v_exp_f32_e32 v81, v210
	v_exp_f32_e32 v79, v50
	v_pk_add_f32 v[18:19], v[82:83], 0 op_sel_hi:[1,0]
	v_exp_f32_e32 v95, v211
	v_pk_add_f32 v[18:19], v[84:85], v[18:19]
	v_cvt_pk_bf16_f32 v66, v82, v84
	v_pk_add_f32 v[18:19], v[74:75], v[18:19]
	v_cvt_pk_bf16_f32 v67, v74, v70
	v_pk_add_f32 v[18:19], v[70:71], v[18:19]
	v_cvt_pk_bf16_f32 v68, v72, v76
	v_cvt_pk_bf16_f32 v69, v80, v94
	v_pk_add_f32 v[18:19], v[72:73], v[18:19]
	v_mov_b32_e32 v0, v79
	s_setprio 1
	s_waitcnt lgkmcnt(6)
	v_mfma_f32_16x16x32_bf16 v[50:53], v[118:121], v[66:69], v[22:25]
	v_pk_mul_f32 v[20:21], v[36:37], v[0:1] op_sel_hi:[1,0]
	s_waitcnt lgkmcnt(4)
	v_mfma_f32_16x16x32_bf16 v[54:57], v[122:125], v[66:69], v[26:29]
	v_cvt_pk_bf16_f32 v22, v83, v85
	v_cvt_pk_bf16_f32 v23, v75, v71
	v_cvt_pk_bf16_f32 v24, v73, v77
	v_pk_add_f32 v[26:27], v[76:77], v[18:19]
	v_pk_mul_f32 v[18:19], v[34:35], v[0:1] op_sel_hi:[1,0]
	v_cvt_pk_bf16_f32 v25, v81, v95
	s_waitcnt lgkmcnt(2)
	v_mfma_f32_16x16x32_bf16 v[58:61], v[126:129], v[66:69], v[58:61]
	v_pk_add_f32 v[26:27], v[80:81], v[26:27]
	v_pk_add_f32 v[26:27], v[94:95], v[26:27]
	v_mfma_f32_16x16x32_bf16 v[34:37], v[118:121], v[22:25], v[18:21]
	v_fma_f32 v88, v88, v78, v26
	v_fma_f32 v89, v89, v79, v27
	s_nop 0
	v_pk_mul_f32 v[20:21], v[40:41], v[0:1] op_sel_hi:[1,0]
	v_pk_mul_f32 v[18:19], v[38:39], v[0:1] op_sel_hi:[1,0]
	s_waitcnt lgkmcnt(0)
	v_mfma_f32_16x16x32_bf16 v[62:65], v[130:133], v[66:69], v[62:65]
	v_mfma_f32_16x16x32_bf16 v[38:41], v[122:125], v[22:25], v[18:21]
	s_setprio 0
	s_nop 2
	v_pk_mul_f32 v[20:21], v[44:45], v[0:1] op_sel_hi:[1,0]
	v_pk_mul_f32 v[18:19], v[42:43], v[0:1] op_sel_hi:[1,0]
	s_nop 1
	v_mfma_f32_16x16x32_bf16 v[42:45], v[126:129], v[22:25], v[18:21]
	s_nop 2
	v_pk_mul_f32 v[20:21], v[48:49], v[0:1] op_sel_hi:[1,0]
	v_pk_mul_f32 v[18:19], v[46:47], v[0:1] op_sel_hi:[1,0]
	s_nop 1
	v_mfma_f32_16x16x32_bf16 v[46:49], v[130:133], v[22:25], v[18:21]
